# layer-0 w_in GEMM main tiles: XCDs 3 decode positions apart (was 6 in the previous version, 12 originally)
# baseline (speedup 1.0000x reference)
.Lgi_sk_rot0:
	s_and_b32 s0, s54, 7
	s_lshr_b32 s1, s54, 3
	s_mul_i32 s57, s0, 183
	s_add_u32 s1, s1, s57
	s_mul_i32 s57, s1, 0x5556
	s_lshr_b32 s57, s57, 22
	s_mul_i32 s57, s57, 192
	s_sub_u32 s1, s1, s57
	s_lshl_b32 s1, s1, 3
	s_or_b32 s57, s1, s0
	s_branch .Lgi_sk_dec
